# phase 0 no longer copies x into the residual buffer H; layer 0's out-projection reads its residual from x and writes H (saves a 67 MB write)
# speedup vs baseline: 1.0134x; 1.0080x over previous
; __device__ void rmsnorm_rows(const float* src, const float* gw, bf16_t* dst, float* copy, unsigned char* dst8 = nullptr) {
;     ...
;     for (int rr = 0; rr < 4; ++rr) {
;       const int row = row0 + rr * stride;
;       if (row < T_TOK) {
;         float ss = 0.f;
; #pragma unroll
;         for (int k = 0; k < 4; ++k) ss += v[rr][k].x * v[rr][k].x + v[rr][k].y * v[rr][k].y + v[rr][k].z * v[rr][k].z + v[rr][k].w * v[rr][k].w;
;         ss = wavesum_f(ss);
;         const float rs = rsqrtf(ss * (1.f / 1024.f) + 1e-6f);
; #pragma unroll
;         for (int k = 0; k < 4; ++k) {
;           const f32x4 y = v[rr][k] * rs * gg[k];
;           u32x2 o;
;           o.x = pk_bf16(y.x, y.y);
;           o.y = pk_bf16(y.z, y.w);
;           if (dst) ((u32x2*)(dst + (size_t)row * 1024))[lane + 64 * k] = o;
;           if (dst8) {
;             int wd = __builtin_amdgcn_cvt_pk_fp8_f32(y.x, y.y, 0, false);
;             wd = __builtin_amdgcn_cvt_pk_fp8_f32(y.z, y.w, wd, true);
;             ((int*)(dst8 + (size_t)row * 1024))[lane + 64 * k] = wd;
;           }
;           if (copy) ((f32x4*)(copy + (size_t)row * 1024))[lane + 64 * k] = v[rr][k];
.LBB0_43:
	s_or_b64 exec, exec, s[8:9]
	s_waitcnt vmcnt(3)
	v_mov_b32_e32 v114, v79
	s_waitcnt vmcnt(2)
	v_mov_b32_e32 v115, v75
	v_mov_b32_e32 v112, v78
	v_mov_b32_e32 v113, v74
	v_pk_mul_f32 v[114:115], v[114:115], v[114:115]
	s_waitcnt vmcnt(1)
	v_mov_b32_e32 v116, v71
	v_pk_fma_f32 v[112:113], v[112:113], v[112:113], v[114:115]
	v_mov_b32_e32 v114, v80
	v_mov_b32_e32 v115, v76
	v_pk_fma_f32 v[112:113], v[114:115], v[114:115], v[112:113]
	v_mov_b32_e32 v114, v81
	v_mov_b32_e32 v115, v77
	s_waitcnt vmcnt(0)
	v_mov_b32_e32 v117, v67
	v_pk_fma_f32 v[112:113], v[114:115], v[114:115], v[112:113]
	v_mov_b32_e32 v114, v70
	v_mov_b32_e32 v115, v66
	v_pk_mul_f32 v[116:117], v[116:117], v[116:117]
	v_add_f32_e32 v83, v112, v113
	v_pk_fma_f32 v[114:115], v[114:115], v[114:115], v[116:117]
	v_mov_b32_e32 v116, v72
	v_mov_b32_e32 v117, v68
	v_pk_fma_f32 v[114:115], v[116:117], v[116:117], v[114:115]
	v_mov_b32_e32 v116, v73
	v_mov_b32_e32 v117, v69
	v_pk_fma_f32 v[114:115], v[116:117], v[116:117], v[114:115]
	v_lshl_add_u64 v[118:119], v[100:101], 0, v[98:99]
	v_add_f32_e32 v83, v83, v114
	v_add_f32_e32 v83, v83, v115
	s_nop 1
	v_add_f32_dpp v83, v83, v83 row_ror:1 row_mask:0xf bank_mask:0xf bound_ctrl:1
	s_nop 1
	v_add_f32_dpp v83, v83, v83 row_ror:2 row_mask:0xf bank_mask:0xf bound_ctrl:1
	s_nop 1
	v_add_f32_dpp v83, v83, v83 row_ror:4 row_mask:0xf bank_mask:0xf bound_ctrl:1
	s_nop 1
	v_add_f32_dpp v83, v83, v83 row_ror:8 row_mask:0xf bank_mask:0xf bound_ctrl:1
	s_nop 0
	v_readlane_b32 s9, v83, 16
	v_readlane_b32 s8, v83, 0
	s_nop 0
	v_mov_b32_e32 v111, s9
	v_add_f32_e32 v111, s8, v111
	v_readlane_b32 s8, v83, 32
	s_nop 1
	v_add_f32_e32 v111, s8, v111
	v_readlane_b32 s8, v83, 48
	s_nop 1
	v_add_f32_e32 v83, s8, v111
	v_fmamk_f32 v83, v83, 0x3a800000, v1
	v_mul_f32_e32 v111, 0x4b800000, v83
	v_cmp_gt_f32_e64 s[8:9], s4, v83
	s_nop 1
	v_cndmask_b32_e64 v83, v83, v111, s[8:9]
	v_rsq_f32_e32 v83, v83
	s_nop 0
	v_mul_f32_e32 v111, 0x45800000, v83
	v_cndmask_b32_e64 v112, v83, v111, s[8:9]
	v_pk_mul_f32 v[114:115], v[78:79], v[112:113] op_sel_hi:[1,0]
	v_pk_mul_f32 v[116:117], v[80:81], v[112:113] op_sel_hi:[1,0]
	v_pk_mul_f32 v[114:115], v[2:3], v[114:115]
	v_pk_mul_f32 v[116:117], v[4:5], v[116:117]
	v_cvt_pk_bf16_f32 v114, v114, v115
	v_cvt_pk_bf16_f32 v115, v116, v117
	global_store_dwordx2 v[118:119], v[114:115], off offset:-1024
	v_lshl_add_u64 v[114:115], v[96:97], 0, v[84:85]
	v_add_co_u32_e64 v114, s[8:9], s5, v114
	s_nop 1
	v_addc_co_u32_e64 v115, s[8:9], 0, v115, s[8:9]
	s_nop 1
	v_pk_mul_f32 v[78:79], v[74:75], v[112:113] op_sel_hi:[1,0]
	v_pk_mul_f32 v[80:81], v[76:77], v[112:113] op_sel_hi:[1,0]
	v_pk_mul_f32 v[78:79], v[6:7], v[78:79]
	v_pk_mul_f32 v[80:81], v[8:9], v[80:81]
	v_cvt_pk_bf16_f32 v78, v78, v79
	v_cvt_pk_bf16_f32 v79, v80, v81
	global_store_dwordx2 v[118:119], v[78:79], off offset:-512
	s_nop 1
	v_pk_mul_f32 v[74:75], v[70:71], v[112:113] op_sel_hi:[1,0]
	v_pk_mul_f32 v[76:77], v[72:73], v[112:113] op_sel_hi:[1,0]
	v_pk_mul_f32 v[74:75], v[10:11], v[74:75]
	v_pk_mul_f32 v[76:77], v[12:13], v[76:77]
	v_cvt_pk_bf16_f32 v74, v74, v75
	v_cvt_pk_bf16_f32 v75, v76, v77
	global_store_dwordx2 v[118:119], v[74:75], off
	s_nop 1
	v_pk_mul_f32 v[70:71], v[66:67], v[112:113] op_sel_hi:[1,0]
	v_pk_mul_f32 v[72:73], v[68:69], v[112:113] op_sel_hi:[1,0]
	v_pk_mul_f32 v[70:71], v[14:15], v[70:71]
	v_pk_mul_f32 v[72:73], v[16:17], v[72:73]
	v_cvt_pk_bf16_f32 v70, v70, v71
	v_cvt_pk_bf16_f32 v71, v72, v73
	global_store_dwordx2 v[118:119], v[70:71], off offset:512
	s_and_saveexec_b64 s[8:9], s[6:7]
	s_cbranch_execz .LBB0_46
	v_mov_b32_e32 v68, v59
	v_mov_b32_e32 v69, v63
	v_mov_b32_e32 v66, v58
	v_mov_b32_e32 v67, v62
	v_pk_mul_f32 v[68:69], v[68:69], v[68:69]
	v_mov_b32_e32 v70, v51
	v_pk_fma_f32 v[66:67], v[66:67], v[66:67], v[68:69]
	v_mov_b32_e32 v68, v60
	v_mov_b32_e32 v69, v64
	v_pk_fma_f32 v[66:67], v[68:69], v[68:69], v[66:67]
	v_mov_b32_e32 v68, v61
	v_mov_b32_e32 v69, v65
	v_mov_b32_e32 v71, v55
	v_pk_fma_f32 v[66:67], v[68:69], v[68:69], v[66:67]
	v_mov_b32_e32 v68, v50
	v_mov_b32_e32 v69, v54
	v_pk_mul_f32 v[70:71], v[70:71], v[70:71]
	v_add_f32_e32 v66, v66, v67
	v_pk_fma_f32 v[68:69], v[68:69], v[68:69], v[70:71]
	v_mov_b32_e32 v70, v52
	v_mov_b32_e32 v71, v56
	v_pk_fma_f32 v[68:69], v[70:71], v[70:71], v[68:69]
	v_mov_b32_e32 v70, v53
	v_mov_b32_e32 v71, v57
	v_pk_fma_f32 v[68:69], v[70:71], v[70:71], v[68:69]
	v_lshl_add_u64 v[72:73], v[100:101], 0, v[102:103]
	v_add_f32_e32 v66, v69, v66
	v_add_f32_e32 v66, v68, v66
	s_nop 1
	v_add_f32_dpp v66, v66, v66 row_ror:1 row_mask:0xf bank_mask:0xf bound_ctrl:1
	s_nop 1
	v_add_f32_dpp v66, v66, v66 row_ror:2 row_mask:0xf bank_mask:0xf bound_ctrl:1
	s_nop 1
	v_add_f32_dpp v66, v66, v66 row_ror:4 row_mask:0xf bank_mask:0xf bound_ctrl:1
	s_nop 1
	v_add_f32_dpp v66, v66, v66 row_ror:8 row_mask:0xf bank_mask:0xf bound_ctrl:1
	s_nop 0
	v_readlane_b32 s7, v66, 16
	v_readlane_b32 s6, v66, 0
	s_nop 0
	v_mov_b32_e32 v67, s7
	v_add_f32_e32 v67, s6, v67
	v_readlane_b32 s6, v66, 32
	s_nop 1
	v_add_f32_e32 v67, s6, v67
	v_readlane_b32 s6, v66, 48
	s_nop 1
	v_add_f32_e32 v66, s6, v67
	v_fmamk_f32 v66, v66, 0x3a800000, v1
	v_mul_f32_e32 v67, 0x4b800000, v66
	v_cmp_gt_f32_e64 s[6:7], s4, v66
	s_nop 1
	v_cndmask_b32_e64 v66, v66, v67, s[6:7]
	v_rsq_f32_e32 v66, v66
	s_nop 0
	v_mul_f32_e32 v67, 0x45800000, v66
	v_cndmask_b32_e64 v66, v66, v67, s[6:7]
	v_pk_mul_f32 v[68:69], v[62:63], v[66:67] op_sel_hi:[1,0]
	v_pk_mul_f32 v[70:71], v[64:65], v[66:67] op_sel_hi:[1,0]
	v_pk_mul_f32 v[68:69], v[2:3], v[68:69]
	v_pk_mul_f32 v[70:71], v[4:5], v[70:71]
	v_cvt_pk_bf16_f32 v68, v68, v69
	v_cvt_pk_bf16_f32 v69, v70, v71
	global_store_dwordx2 v[72:73], v[68:69], off offset:-1024
	v_lshl_add_u64 v[68:69], v[92:93], 0, v[84:85]
	v_pk_mul_f32 v[70:71], v[58:59], v[66:67] op_sel_hi:[1,0]
	v_pk_mul_f32 v[74:75], v[60:61], v[66:67] op_sel_hi:[1,0]
	v_add_co_u32_e64 v68, s[6:7], s5, v68
	v_pk_mul_f32 v[74:75], v[8:9], v[74:75]
	v_pk_mul_f32 v[70:71], v[6:7], v[70:71]
	v_addc_co_u32_e64 v69, s[6:7], 0, v69, s[6:7]
	v_cvt_pk_bf16_f32 v70, v70, v71
	v_cvt_pk_bf16_f32 v71, v74, v75
	global_store_dwordx2 v[72:73], v[70:71], off offset:-512
	v_pk_mul_f32 v[70:71], v[54:55], v[66:67] op_sel_hi:[1,0]
	v_pk_mul_f32 v[74:75], v[56:57], v[66:67] op_sel_hi:[1,0]
	v_pk_mul_f32 v[70:71], v[10:11], v[70:71]
	v_pk_mul_f32 v[74:75], v[12:13], v[74:75]
	v_cvt_pk_bf16_f32 v70, v70, v71
	v_cvt_pk_bf16_f32 v71, v74, v75
	global_store_dwordx2 v[72:73], v[70:71], off
	v_pk_mul_f32 v[70:71], v[50:51], v[66:67] op_sel_hi:[1,0]
	v_pk_mul_f32 v[66:67], v[52:53], v[66:67] op_sel_hi:[1,0]
	v_pk_mul_f32 v[70:71], v[14:15], v[70:71]
	v_pk_mul_f32 v[66:67], v[16:17], v[66:67]
	v_cvt_pk_bf16_f32 v70, v70, v71
	v_cvt_pk_bf16_f32 v71, v66, v67
	global_store_dwordx2 v[72:73], v[70:71], off offset:512
	s_or_b64 exec, exec, s[8:9]
	s_and_saveexec_b64 s[6:7], s[0:1]
	s_cbranch_execnz .LBB0_47

; __device__ void rmsnorm_rows(const float* src, const float* gw, bf16_t* dst, float* copy, unsigned char* dst8 = nullptr) {
;     ...
;     for (int rr = 0; rr < 4; ++rr) {
;       const int row = row0 + rr * stride;
;       if (row < T_TOK) {
;         float ss = 0.f;
; #pragma unroll
;         for (int k = 0; k < 4; ++k) ss += v[rr][k].x * v[rr][k].x + v[rr][k].y * v[rr][k].y + v[rr][k].z * v[rr][k].z + v[rr][k].w * v[rr][k].w;
;         ss = wavesum_f(ss);
;         const float rs = rsqrtf(ss * (1.f / 1024.f) + 1e-6f);
; #pragma unroll
;         for (int k = 0; k < 4; ++k) {
;           const f32x4 y = v[rr][k] * rs * gg[k];
;           u32x2 o;
;           o.x = pk_bf16(y.x, y.y);
;           o.y = pk_bf16(y.z, y.w);
;           if (dst) ((u32x2*)(dst + (size_t)row * 1024))[lane + 64 * k] = o;
;           if (dst8) {
;             int wd = __builtin_amdgcn_cvt_pk_fp8_f32(y.x, y.y, 0, false);
;             wd = __builtin_amdgcn_cvt_pk_fp8_f32(y.z, y.w, wd, true);
;             ((int*)(dst8 + (size_t)row * 1024))[lane + 64 * k] = wd;
;           }
;           if (copy) ((f32x4*)(copy + (size_t)row * 1024))[lane + 64 * k] = v[rr][k];
.LBB0_47:
	v_mov_b32_e32 v68, v43
	v_mov_b32_e32 v69, v47
	v_mov_b32_e32 v66, v42
	v_mov_b32_e32 v67, v46
	v_pk_mul_f32 v[68:69], v[68:69], v[68:69]
	v_mov_b32_e32 v70, v35
	v_pk_fma_f32 v[66:67], v[66:67], v[66:67], v[68:69]
	v_mov_b32_e32 v68, v44
	v_mov_b32_e32 v69, v48
	v_pk_fma_f32 v[66:67], v[68:69], v[68:69], v[66:67]
	v_mov_b32_e32 v68, v45
	v_mov_b32_e32 v69, v49
	v_mov_b32_e32 v71, v39
	v_pk_fma_f32 v[66:67], v[68:69], v[68:69], v[66:67]
	v_mov_b32_e32 v68, v34
	v_mov_b32_e32 v69, v38
	v_pk_mul_f32 v[70:71], v[70:71], v[70:71]
	v_add_f32_e32 v66, v66, v67
	v_pk_fma_f32 v[68:69], v[68:69], v[68:69], v[70:71]
	v_mov_b32_e32 v70, v36
	v_mov_b32_e32 v71, v40
	v_pk_fma_f32 v[68:69], v[70:71], v[70:71], v[68:69]
	v_mov_b32_e32 v70, v37
	v_mov_b32_e32 v71, v41
	v_pk_fma_f32 v[68:69], v[70:71], v[70:71], v[68:69]
	v_lshlrev_b64 v[70:71], 12, v[108:109]
	v_add_f32_e32 v66, v69, v66
	v_add_f32_e32 v66, v68, v66
	v_lshlrev_b64 v[68:69], 11, v[108:109]
	v_lshl_add_u64 v[68:69], v[88:89], 0, v[68:69]
	v_add_f32_dpp v66, v66, v66 row_ror:1 row_mask:0xf bank_mask:0xf bound_ctrl:1
	v_lshl_add_u64 v[70:71], v[90:91], 0, v[70:71]
	s_nop 0
	v_add_f32_dpp v66, v66, v66 row_ror:2 row_mask:0xf bank_mask:0xf bound_ctrl:1
	s_nop 1
	v_add_f32_dpp v66, v66, v66 row_ror:4 row_mask:0xf bank_mask:0xf bound_ctrl:1
	s_nop 1
	v_add_f32_dpp v66, v66, v66 row_ror:8 row_mask:0xf bank_mask:0xf bound_ctrl:1
	s_nop 0
	v_readlane_b32 s1, v66, 16
	v_readlane_b32 s0, v66, 0
	s_nop 0
	v_mov_b32_e32 v67, s1
	v_add_f32_e32 v67, s0, v67
	v_readlane_b32 s0, v66, 32
	s_nop 1
	v_add_f32_e32 v67, s0, v67
	v_readlane_b32 s0, v66, 48
	s_nop 1
	v_add_f32_e32 v66, s0, v67
	v_fmamk_f32 v66, v66, 0x3a800000, v1
	v_mul_f32_e32 v67, 0x4b800000, v66
	v_cmp_gt_f32_e64 s[0:1], s4, v66
	s_nop 1
	v_cndmask_b32_e64 v66, v66, v67, s[0:1]
	v_rsq_f32_e32 v66, v66
	s_nop 0
	v_mul_f32_e32 v67, 0x45800000, v66
	v_cndmask_b32_e64 v66, v66, v67, s[0:1]
	v_pk_mul_f32 v[72:73], v[46:47], v[66:67] op_sel_hi:[1,0]
	v_pk_mul_f32 v[74:75], v[48:49], v[66:67] op_sel_hi:[1,0]
	v_pk_mul_f32 v[72:73], v[2:3], v[72:73]
	v_pk_mul_f32 v[74:75], v[4:5], v[74:75]
	v_cvt_pk_bf16_f32 v72, v72, v73
	v_cvt_pk_bf16_f32 v73, v74, v75
	global_store_dwordx2 v[68:69], v[72:73], off
	v_pk_mul_f32 v[72:73], v[42:43], v[66:67] op_sel_hi:[1,0]
	v_pk_mul_f32 v[74:75], v[44:45], v[66:67] op_sel_hi:[1,0]
	v_pk_mul_f32 v[72:73], v[6:7], v[72:73]
	v_pk_mul_f32 v[74:75], v[8:9], v[74:75]
	v_cvt_pk_bf16_f32 v72, v72, v73
	v_cvt_pk_bf16_f32 v73, v74, v75
	global_store_dwordx2 v[68:69], v[72:73], off offset:512
	v_pk_mul_f32 v[72:73], v[38:39], v[66:67] op_sel_hi:[1,0]
	v_pk_mul_f32 v[74:75], v[40:41], v[66:67] op_sel_hi:[1,0]
	v_pk_mul_f32 v[72:73], v[10:11], v[72:73]
	v_pk_mul_f32 v[74:75], v[12:13], v[74:75]
	v_cvt_pk_bf16_f32 v72, v72, v73
	v_cvt_pk_bf16_f32 v73, v74, v75
	global_store_dwordx2 v[68:69], v[72:73], off offset:1024
	v_pk_mul_f32 v[72:73], v[34:35], v[66:67] op_sel_hi:[1,0]
	v_pk_mul_f32 v[66:67], v[36:37], v[66:67] op_sel_hi:[1,0]
	v_pk_mul_f32 v[72:73], v[14:15], v[72:73]
	v_pk_mul_f32 v[66:67], v[16:17], v[66:67]
	v_cvt_pk_bf16_f32 v72, v72, v73
	v_cvt_pk_bf16_f32 v73, v66, v67
	global_store_dwordx2 v[68:69], v[72:73], off offset:1536
	s_or_b64 exec, exec, s[6:7]
	s_and_saveexec_b64 s[0:1], vcc
	s_cbranch_execz .LBB0_36
.LBB0_48:
	v_mov_b32_e32 v68, v27
	v_mov_b32_e32 v69, v31
	v_mov_b32_e32 v66, v26
	v_mov_b32_e32 v67, v30
	v_pk_mul_f32 v[68:69], v[68:69], v[68:69]
	v_mov_b32_e32 v70, v19
	v_pk_fma_f32 v[66:67], v[66:67], v[66:67], v[68:69]
	v_mov_b32_e32 v68, v28
	v_mov_b32_e32 v69, v32
	v_pk_fma_f32 v[66:67], v[68:69], v[68:69], v[66:67]
	v_mov_b32_e32 v68, v29
	v_mov_b32_e32 v69, v33
	v_mov_b32_e32 v71, v23
	v_pk_fma_f32 v[66:67], v[68:69], v[68:69], v[66:67]
	v_mov_b32_e32 v68, v18
	v_mov_b32_e32 v69, v22
	v_pk_mul_f32 v[70:71], v[70:71], v[70:71]
	v_add_f32_e32 v66, v66, v67
	v_pk_fma_f32 v[68:69], v[68:69], v[68:69], v[70:71]
	v_mov_b32_e32 v70, v20
	v_mov_b32_e32 v71, v24
	v_pk_fma_f32 v[68:69], v[70:71], v[70:71], v[68:69]
	v_mov_b32_e32 v70, v21
	v_mov_b32_e32 v71, v25
	v_pk_fma_f32 v[68:69], v[70:71], v[70:71], v[68:69]
	v_lshlrev_b64 v[70:71], 12, v[106:107]
	v_add_f32_e32 v66, v69, v66
	v_add_f32_e32 v66, v68, v66
	v_lshlrev_b64 v[68:69], 11, v[106:107]
	v_lshl_add_u64 v[68:69], v[88:89], 0, v[68:69]
	v_add_f32_dpp v66, v66, v66 row_ror:1 row_mask:0xf bank_mask:0xf bound_ctrl:1
	v_lshl_add_u64 v[70:71], v[90:91], 0, v[70:71]
	s_nop 0
	v_add_f32_dpp v66, v66, v66 row_ror:2 row_mask:0xf bank_mask:0xf bound_ctrl:1
	s_nop 1
	v_add_f32_dpp v66, v66, v66 row_ror:4 row_mask:0xf bank_mask:0xf bound_ctrl:1
	s_nop 1
	v_add_f32_dpp v66, v66, v66 row_ror:8 row_mask:0xf bank_mask:0xf bound_ctrl:1
	s_nop 0
	v_readlane_b32 s7, v66, 16
	v_readlane_b32 s6, v66, 0
	s_nop 0
	v_mov_b32_e32 v67, s7
	v_add_f32_e32 v67, s6, v67
	v_readlane_b32 s6, v66, 32
	s_nop 1
	v_add_f32_e32 v67, s6, v67
	v_readlane_b32 s6, v66, 48
	s_nop 1
	v_add_f32_e32 v66, s6, v67
	v_fmamk_f32 v66, v66, 0x3a800000, v1
	v_mul_f32_e32 v67, 0x4b800000, v66
	v_cmp_gt_f32_e32 vcc, s4, v66
	s_nop 1
	v_cndmask_b32_e32 v66, v66, v67, vcc
	v_rsq_f32_e32 v66, v66
	s_nop 0
	v_mul_f32_e32 v67, 0x45800000, v66
	v_cndmask_b32_e32 v66, v66, v67, vcc
	v_pk_mul_f32 v[72:73], v[30:31], v[66:67] op_sel_hi:[1,0]
	v_pk_mul_f32 v[74:75], v[32:33], v[66:67] op_sel_hi:[1,0]
	v_pk_mul_f32 v[72:73], v[2:3], v[72:73]
	v_pk_mul_f32 v[74:75], v[4:5], v[74:75]
	v_cvt_pk_bf16_f32 v72, v72, v73
	v_cvt_pk_bf16_f32 v73, v74, v75
	global_store_dwordx2 v[68:69], v[72:73], off
	v_pk_mul_f32 v[72:73], v[26:27], v[66:67] op_sel_hi:[1,0]
	v_pk_mul_f32 v[74:75], v[28:29], v[66:67] op_sel_hi:[1,0]
	v_pk_mul_f32 v[72:73], v[6:7], v[72:73]
	v_pk_mul_f32 v[74:75], v[8:9], v[74:75]
	v_cvt_pk_bf16_f32 v72, v72, v73
	v_cvt_pk_bf16_f32 v73, v74, v75
	global_store_dwordx2 v[68:69], v[72:73], off offset:512
	v_pk_mul_f32 v[72:73], v[22:23], v[66:67] op_sel_hi:[1,0]
	v_pk_mul_f32 v[74:75], v[24:25], v[66:67] op_sel_hi:[1,0]
	v_pk_mul_f32 v[72:73], v[10:11], v[72:73]
	v_pk_mul_f32 v[74:75], v[12:13], v[74:75]
	v_cvt_pk_bf16_f32 v72, v72, v73
	v_cvt_pk_bf16_f32 v73, v74, v75
	global_store_dwordx2 v[68:69], v[72:73], off offset:1024
	v_pk_mul_f32 v[72:73], v[18:19], v[66:67] op_sel_hi:[1,0]
	v_pk_mul_f32 v[66:67], v[20:21], v[66:67] op_sel_hi:[1,0]
	v_pk_mul_f32 v[72:73], v[14:15], v[72:73]
	v_pk_mul_f32 v[66:67], v[16:17], v[66:67]
	v_cvt_pk_bf16_f32 v72, v72, v73
	v_cvt_pk_bf16_f32 v73, v66, v67
	global_store_dwordx2 v[68:69], v[72:73], off offset:1536
	s_branch .LBB0_36

; __device__ __forceinline__ int otid() { int t = threadIdx.x; asm volatile("" : "+v"(t)); return t; }
; template <int MI, bool SWAP, bool F8 = false>
; __device__ __forceinline__ void gemm_core(const bf16_t* __restrict__ A, int lda, const bf16_t* __restrict__ B, int ldb,
;                                           int K, char* smem, f32x4 (&acc)[MI][4]) {
;   const int tid = otid(), lane = tid & 63, w = tid >> 6, wm = w >> 1, wn = w & 1;
;   const int lr = tid >> 3, lc = tid & 7;
;   const int li = lane & 15, g = lane >> 4;
;   u32x4 ra[MI], rb[4];
;   const bf16_t* ap = A + (size_t)lr * lda + lc * 8;
;   const bf16_t* bp = B + (size_t)lr * ldb + lc * 8;
; #pragma unroll
;   for (int i = 0; i < MI; ++i)
; #pragma unroll
;     for (int j = 0; j < 4; ++j) acc[i][j] = (f32x4){0.f, 0.f, 0.f, 0.f};
;   const int nk = K >> 6;
; #pragma unroll
;   for (int i = 0; i < MI; ++i) ra[i] = *(const u32x4*)(ap + (size_t)(32 * i) * lda);
; #pragma unroll
;   for (int i = 0; i < 4; ++i) rb[i] = *(const u32x4*)(bp + (size_t)(32 * i) * ldb);
;   const int woff = lr * 128 + ((lc ^ (lr & 7)) << 4);
;   const int xrow = (wm * 16 * MI + li) * 128;
;   const int wrow = 32768 + (wn * 32 + li) * 128;
; __global__ void __launch_bounds__(256, 2) fwd_kernel(P p) {
;     ...
;       for (int it = blockIdx.x; it < 64 * 8; it += G) {
;         const int tm = (it & 7) * 8 + ((it >> 3) >> 3), tn = (it >> 3) & 7;
;         gemm_tile_f32<true, 8>((const bf16_t*)(ws + OFF_AO) + (size_t)tm * 256 * 1024, 1024,
;                             (const bf16_t*)(ws + OFF_WEOUT) + ((size_t)li2 * 1024 + tn * 128) * 1024, 1024, 1024,
;                             H + (size_t)tm * 256 * 1024 + tn * 128, 1024, smem);
.LBB0_818:
	s_lshl_b32 s0, s19, 10
	s_and_b32 s0, s0, 0xe0000
	s_add_i32 s66, s8, s0
	s_lshl_b32 s0, s21, 3
	s_and_b32 s0, s0, 56
	s_ashr_i32 s29, s21, 6
	s_add_i32 s22, s0, s29
	s_ashr_i32 s23, s22, 31
	s_waitcnt vmcnt(17)
	v_mov_b32_e32 v30, v208
	s_and_b32 s28, s20, 56
	s_lshl_b64 s[6:7], s[66:67], 1
	s_lshl_b64 s[0:1], s[22:23], 18
	s_lshl_b64 s[22:23], s[22:23], 19
	s_add_u32 s24, s9, s22
	v_ashrrev_i32_e32 v2, 3, v30
	v_ashrrev_i32_e32 v3, 31, v2
	s_addc_u32 s25, s10, s23
	v_lshlrev_b64 v[20:21], 11, v[2:3]
	v_lshlrev_b32_e32 v0, 4, v30
	v_lshl_add_u64 v[24:25], s[24:25], 0, v[20:21]
	v_and_b32_e32 v0, 0x70, v0
	v_lshl_add_u64 v[24:25], v[24:25], 0, v[0:1]
	v_add_co_u32_e32 v26, vcc, s93, v24
	s_lshl_b32 s22, s21, 4
	s_nop 0
	v_addc_co_u32_e32 v27, vcc, 0, v25, vcc
	v_lshrrev_b32_e32 v254, 3, v208
	v_and_b32_e32 v254, 7, v254
	v_xor_b32_e32 v252, v254, v208
	v_and_b32_e32 v252, 7, v252
	v_lshlrev_b32_e32 v252, 4, v252
	v_lshl_or_b32 v252, v254, 11, v252
	v_add_u32_e32 v253, 0x10000, v252
	v_lshrrev_b32_e32 v254, 6, v208
	s_nop 0
	v_readfirstlane_b32 s62, v254
	s_lshl_b32 s62, s62, 10
	v_readfirstlane_b32 s56, v24
	v_readfirstlane_b32 s57, v25
	v_add_co_u32_e32 v26, vcc, s46, v24
	s_and_b32 s22, s22, 0x380
	s_nop 0
	v_addc_co_u32_e32 v27, vcc, 0, v25, vcc
	v_add_co_u32_e32 v28, vcc, s47, v24
	s_lshl_b32 s23, s8, 1
	s_nop 0
	v_addc_co_u32_e32 v29, vcc, 0, v25, vcc
	v_add_co_u32_e32 v26, vcc, s50, v24
	s_lshl_b32 s26, s22, 11
	s_nop 0
	v_addc_co_u32_e32 v27, vcc, 0, v25, vcc
	s_or_b32 s23, s26, s23
	v_add_co_u32_e32 v28, vcc, s51, v24
	s_add_u32 s26, s11, s23
	s_nop 0
	v_addc_co_u32_e32 v29, vcc, 0, v25, vcc
	s_mov_b32 s23, 0x60000
	v_add_co_u32_e32 v26, vcc, s23, v24
	s_addc_u32 s27, s18, 0
	s_nop 0
	v_addc_co_u32_e32 v27, vcc, 0, v25, vcc
	s_mov_b32 s23, 0x70000
	v_lshl_add_u64 v[22:23], s[26:27], 0, v[20:21]
	v_add_co_u32_e32 v24, vcc, s23, v24
	v_lshl_add_u64 v[22:23], v[22:23], 0, v[0:1]
	s_nop 0
	v_addc_co_u32_e32 v25, vcc, 0, v25, vcc
	v_add_co_u32_e32 v24, vcc, s93, v22
	v_lshlrev_b32_e32 v0, 7, v2
	s_nop 0
	v_addc_co_u32_e32 v25, vcc, 0, v23, vcc
	s_nop 0
	v_readfirstlane_b32 s58, v22
	v_readfirstlane_b32 s59, v23
	v_add_co_u32_e32 v24, vcc, s46, v22
	v_xor_b32_e32 v2, v2, v30
	s_nop 0
	v_addc_co_u32_e32 v25, vcc, 0, v23, vcc
	v_add_co_u32_e32 v22, vcc, s47, v22
	v_lshlrev_b32_e32 v2, 4, v2
	s_nop 0
	v_addc_co_u32_e32 v23, vcc, 0, v23, vcc
	v_and_or_b32 v0, v2, s33, v0
	v_lshlrev_b32_e32 v2, 7, v30
	v_and_b32_e32 v3, 15, v30
	v_and_b32_e32 v202, 0xffffc780, v2
	v_lshrrev_b32_e32 v2, 1, v30
	v_lshrrev_b32_e32 v31, 4, v30
	v_and_or_b32 v2, v2, 32, v3
	v_and_b32_e32 v23, 7, v30
	s_add_i32 s24, s29, s28
	v_bfe_u32 v22, v30, 4, 2
	v_lshlrev_b32_e32 v203, 7, v2
	v_bitop3_b32 v2, v31, v23, 3 bitop3:0x6c
	s_ashr_i32 s25, s24, 31
	v_lshlrev_b32_e32 v204, 4, v2
	v_bitop3_b32 v2, v22, v23, 4 bitop3:0x36
	s_lshl_b64 s[24:25], s[24:25], 19
	v_lshlrev_b32_e32 v205, 4, v2
	v_lshl_add_u64 v[2:3], s[24:25], 0, v[20:21]
	v_lshlrev_b32_e32 v22, 4, v23
	s_add_u32 s6, s12, s6
	v_or_b32_e32 v2, v2, v22
	v_or_b32_e32 v20, v20, v22
	s_addc_u32 s7, s13, s7
	v_mov_b32_e32 v144, 0
	v_lshl_add_u64 v[2:3], s[12:13], 0, v[2:3]
	v_lshl_add_u64 v[200:201], s[6:7], 0, v[20:21]
	s_mov_b64 s[6:7], 0
	v_mov_b32_e32 v145, v144
	v_mov_b32_e32 v146, v144
	v_mov_b32_e32 v147, v144
	s_waitcnt vmcnt(24)
	v_mov_b32_e32 v100, v144
	v_mov_b32_e32 v101, v144
	v_mov_b32_e32 v102, v144
	v_mov_b32_e32 v103, v144
	v_mov_b32_e32 v112, v144
	v_mov_b32_e32 v113, v144
	v_mov_b32_e32 v114, v144
	v_mov_b32_e32 v115, v144
	s_waitcnt vmcnt(23)
; template <bool ACCUM, int MI>
; __device__ void gemm_tile_f32(const bf16_t* A, int lda, const bf16_t* B, int ldb, int K, float* C, int ldc, char* smem) {
;     ...
;       f32x4* cp = (f32x4*)(C + (size_t)MROW(i) * ldc + NCOL(j));
;       f32x4 v = acc[i][j];
;       if (ACCUM) v += *cp;
;       *cp = v;
; __global__ void __launch_bounds__(256, 2) fwd_kernel(P p) {
;     ...
;         gemm_tile_f32<true, 8>((const bf16_t*)(ws + OFF_AO) + (size_t)tm * 256 * 1024, 1024,
;                             (const bf16_t*)(ws + OFF_WEOUT) + ((size_t)li2 * 1024 + tn * 128) * 1024, 1024, 1024,
;                             H + (size_t)tm * 256 * 1024 + tn * 128, 1024, smem);
	v_mov_b32_e32 v116, v144
	v_mov_b32_e32 v117, v144
	v_mov_b32_e32 v118, v144
	v_mov_b32_e32 v119, v144
	s_waitcnt vmcnt(22)
	v_mov_b32_e32 v120, v144
	v_mov_b32_e32 v121, v144
	v_mov_b32_e32 v122, v144
	v_mov_b32_e32 v123, v144
	s_waitcnt vmcnt(20)
	v_mov_b32_e32 v128, v144
	v_mov_b32_e32 v129, v144
	v_mov_b32_e32 v130, v144
	v_mov_b32_e32 v131, v144
	v_mov_b32_e32 v76, v144
	v_mov_b32_e32 v77, v144
	v_mov_b32_e32 v78, v144
	v_mov_b32_e32 v79, v144
	v_mov_b32_e32 v72, v144
	v_mov_b32_e32 v73, v144
	v_mov_b32_e32 v74, v144
	v_mov_b32_e32 v75, v144
	v_mov_b32_e32 v64, v144
	v_mov_b32_e32 v65, v144
	v_mov_b32_e32 v66, v144
	v_mov_b32_e32 v67, v144
	v_mov_b32_e32 v68, v144
	v_mov_b32_e32 v69, v144
	v_mov_b32_e32 v70, v144
	v_mov_b32_e32 v71, v144
	v_mov_b32_e32 v20, v144
	v_mov_b32_e32 v21, v144
	v_mov_b32_e32 v22, v144
	v_mov_b32_e32 v23, v144
	v_mov_b32_e32 v24, v144
	v_mov_b32_e32 v25, v144
	v_mov_b32_e32 v26, v144
	v_mov_b32_e32 v27, v144
	v_mov_b32_e32 v28, v144
	v_mov_b32_e32 v29, v144
	v_mov_b32_e32 v30, v144
	v_mov_b32_e32 v31, v144
	v_mov_b32_e32 v32, v144
	v_mov_b32_e32 v33, v144
	v_mov_b32_e32 v34, v144
	v_mov_b32_e32 v35, v144
	v_mov_b32_e32 v36, v144
	v_mov_b32_e32 v37, v144
	v_mov_b32_e32 v38, v144
	v_mov_b32_e32 v39, v144
	v_mov_b32_e32 v40, v144
	v_mov_b32_e32 v41, v144
	v_mov_b32_e32 v42, v144
	v_mov_b32_e32 v43, v144
	v_mov_b32_e32 v44, v144
	v_mov_b32_e32 v45, v144
	v_mov_b32_e32 v46, v144
	v_mov_b32_e32 v47, v144
	v_mov_b32_e32 v48, v144
	v_mov_b32_e32 v49, v144
	v_mov_b32_e32 v50, v144
	v_mov_b32_e32 v51, v144
	v_mov_b32_e32 v52, v144
	v_mov_b32_e32 v53, v144
	v_mov_b32_e32 v54, v144
	v_mov_b32_e32 v55, v144
	v_mov_b32_e32 v56, v144
	v_mov_b32_e32 v57, v144
	v_mov_b32_e32 v58, v144
	v_mov_b32_e32 v59, v144
	v_mov_b32_e32 v60, v144
	v_mov_b32_e32 v61, v144
	v_mov_b32_e32 v62, v144
	v_mov_b32_e32 v63, v144
	v_mov_b32_e32 v80, v144
	v_mov_b32_e32 v81, v144
	v_mov_b32_e32 v82, v144
	v_mov_b32_e32 v83, v144
	v_mov_b32_e32 v84, v144
	v_mov_b32_e32 v85, v144
	v_mov_b32_e32 v86, v144
	v_mov_b32_e32 v87, v144
	v_mov_b32_e32 v88, v144
	v_mov_b32_e32 v89, v144
	v_mov_b32_e32 v90, v144
	v_mov_b32_e32 v91, v144
	v_mov_b32_e32 v92, v144
	v_mov_b32_e32 v93, v144
	v_mov_b32_e32 v94, v144
	v_mov_b32_e32 v95, v144
	v_mov_b32_e32 v96, v144
	v_mov_b32_e32 v97, v144
	v_mov_b32_e32 v98, v144
	v_mov_b32_e32 v99, v144
	v_mov_b32_e32 v104, v144
	v_mov_b32_e32 v105, v144
	v_mov_b32_e32 v106, v144
	v_mov_b32_e32 v107, v144
	v_mov_b32_e32 v108, v144
	v_mov_b32_e32 v109, v144
	v_mov_b32_e32 v110, v144
	v_mov_b32_e32 v111, v144
	v_mov_b32_e32 v124, v144
	v_mov_b32_e32 v125, v144
	v_mov_b32_e32 v126, v144
	v_mov_b32_e32 v127, v144
	v_mov_b32_e32 v132, v144
	v_mov_b32_e32 v133, v144
	v_mov_b32_e32 v134, v144
	v_mov_b32_e32 v135, v144
	v_mov_b32_e32 v136, v144
	v_mov_b32_e32 v137, v144
	v_mov_b32_e32 v138, v144
	v_mov_b32_e32 v139, v144
	v_mov_b32_e32 v140, v144
	v_mov_b32_e32 v141, v144
	v_mov_b32_e32 v142, v144
	v_mov_b32_e32 v143, v144
	s_lshl_b64 s[98:99], s[0:1], 2
	s_lshl_b32 s63, s22, 2
	s_add_u32 s98, s98, s63
	s_addc_u32 s99, s99, 0
	v_readlane_b32 s63, v255, 60
	v_readlane_b32 s38, v255, 22
	v_readlane_b32 s39, v255, 23
	s_nop 1
	s_cmp_eq_u32 s63, 0
	s_cselect_b32 s38, s38, s16
	s_cselect_b32 s39, s39, s17
	s_add_u32 s38, s38, s98
	s_addc_u32 s39, s39, s99
	s_add_u32 s98, s16, s98
	s_addc_u32 s99, s17, s99
	s_mov_b32 s63, 0
	v_and_b32_e32 v236, 0x8f, v208
	v_lshrrev_b32_e32 v237, 1, v208
	v_lshlrev_b32_e32 v236, 12, v236
	v_and_b32_e32 v237, 32, v237
	v_lshrrev_b32_e32 v254, 2, v208
	s_nop 0
	v_and_or_b32 v237, v254, 12, v237
	s_nop 0
	v_lshl_add_u32 v236, v237, 2, v236
	s_nop 0
	v_mov_b32_e32 v237, v236

; template <bool ACCUM, int MI>
; __device__ void gemm_tile_f32(const bf16_t* A, int lda, const bf16_t* B, int ldb, int K, float* C, int ldc, char* smem) {
;     ...
;   for (int i = 0; i < MI; ++i)
; #pragma unroll
;     for (int j = 0; j < 4; ++j) {
;       f32x4* cp = (f32x4*)(C + (size_t)MROW(i) * ldc + NCOL(j));
;       f32x4 v = acc[i][j];
;       if (ACCUM) v += *cp;
;       *cp = v;
.Lcch819_h0:
	global_load_dwordx4 v[4:7], v236, s[38:39]
	global_load_dwordx4 v[8:11], v236, s[38:39] offset:64
	global_load_dwordx4 v[12:15], v236, s[38:39] offset:256
	global_load_dwordx4 v[16:19], v236, s[38:39] offset:320
	v_add_u32_e32 v236, 0x10000, v236
	global_load_dwordx4 v[232:235], v236, s[38:39]
	global_load_dwordx4 v[176:179], v236, s[38:39] offset:64
	global_load_dwordx4 v[184:187], v236, s[38:39] offset:256
	global_load_dwordx4 v[188:191], v236, s[38:39] offset:320
	v_add_u32_e32 v236, 0x10000, v236
	s_branch .Lcch819_ret
.Lcch819_h1:
	v_pk_add_f32 v[140:141], v[140:141], v[4:5]
	v_pk_add_f32 v[142:143], v[142:143], v[6:7]
	v_pk_add_f32 v[136:137], v[136:137], v[8:9]
	v_pk_add_f32 v[138:139], v[138:139], v[10:11]
	v_pk_add_f32 v[132:133], v[132:133], v[12:13]
	v_pk_add_f32 v[134:135], v[134:135], v[14:15]
	v_pk_add_f32 v[124:125], v[124:125], v[16:17]
	v_pk_add_f32 v[126:127], v[126:127], v[18:19]
	v_pk_add_f32 v[108:109], v[108:109], v[232:233]
	v_pk_add_f32 v[110:111], v[110:111], v[234:235]
	v_pk_add_f32 v[104:105], v[104:105], v[176:177]
	v_pk_add_f32 v[106:107], v[106:107], v[178:179]
	v_pk_add_f32 v[96:97], v[96:97], v[184:185]
	v_pk_add_f32 v[98:99], v[98:99], v[186:187]
	v_pk_add_f32 v[92:93], v[92:93], v[188:189]
	v_pk_add_f32 v[94:95], v[94:95], v[190:191]
	global_load_dwordx4 v[4:7], v236, s[38:39]
	global_load_dwordx4 v[8:11], v236, s[38:39] offset:64
	global_load_dwordx4 v[12:15], v236, s[38:39] offset:256
	global_load_dwordx4 v[16:19], v236, s[38:39] offset:320
	v_add_u32_e32 v236, 0x10000, v236
	global_load_dwordx4 v[232:235], v236, s[38:39]
	global_load_dwordx4 v[176:179], v236, s[38:39] offset:64
	global_load_dwordx4 v[184:187], v236, s[38:39] offset:256
	global_load_dwordx4 v[188:191], v236, s[38:39] offset:320
	v_add_u32_e32 v236, 0x10000, v236
	s_branch .Lcch819_ret
.Lcch819_h2:
	v_pk_add_f32 v[88:89], v[88:89], v[4:5]
	v_pk_add_f32 v[90:91], v[90:91], v[6:7]
	v_pk_add_f32 v[84:85], v[84:85], v[8:9]
	v_pk_add_f32 v[86:87], v[86:87], v[10:11]
	v_pk_add_f32 v[80:81], v[80:81], v[12:13]
	v_pk_add_f32 v[82:83], v[82:83], v[14:15]
	v_pk_add_f32 v[60:61], v[60:61], v[16:17]
	v_pk_add_f32 v[62:63], v[62:63], v[18:19]
	v_pk_add_f32 v[56:57], v[56:57], v[232:233]
	v_pk_add_f32 v[58:59], v[58:59], v[234:235]
	v_pk_add_f32 v[52:53], v[52:53], v[176:177]
	v_pk_add_f32 v[54:55], v[54:55], v[178:179]
	v_pk_add_f32 v[48:49], v[48:49], v[184:185]
	v_pk_add_f32 v[50:51], v[50:51], v[186:187]
	v_pk_add_f32 v[44:45], v[44:45], v[188:189]
	v_pk_add_f32 v[46:47], v[46:47], v[190:191]
	global_load_dwordx4 v[4:7], v236, s[38:39]
	global_load_dwordx4 v[8:11], v236, s[38:39] offset:64
	global_load_dwordx4 v[12:15], v236, s[38:39] offset:256
	global_load_dwordx4 v[16:19], v236, s[38:39] offset:320
	v_add_u32_e32 v236, 0x10000, v236
	global_load_dwordx4 v[232:235], v236, s[38:39]
	global_load_dwordx4 v[176:179], v236, s[38:39] offset:64
	global_load_dwordx4 v[184:187], v236, s[38:39] offset:256
	global_load_dwordx4 v[188:191], v236, s[38:39] offset:320
	v_add_u32_e32 v236, 0x10000, v236
	s_branch .Lcch819_ret
.Lcch819_h3:
	v_pk_add_f32 v[40:41], v[40:41], v[4:5]
	v_pk_add_f32 v[42:43], v[42:43], v[6:7]
	v_pk_add_f32 v[36:37], v[36:37], v[8:9]
	v_pk_add_f32 v[38:39], v[38:39], v[10:11]
	v_pk_add_f32 v[32:33], v[32:33], v[12:13]
	v_pk_add_f32 v[34:35], v[34:35], v[14:15]
	v_pk_add_f32 v[28:29], v[28:29], v[16:17]
	v_pk_add_f32 v[30:31], v[30:31], v[18:19]
	v_pk_add_f32 v[24:25], v[24:25], v[232:233]
	v_pk_add_f32 v[26:27], v[26:27], v[234:235]
	v_pk_add_f32 v[20:21], v[20:21], v[176:177]
	v_pk_add_f32 v[22:23], v[22:23], v[178:179]
	v_pk_add_f32 v[68:69], v[68:69], v[184:185]
	v_pk_add_f32 v[70:71], v[70:71], v[186:187]
	v_pk_add_f32 v[64:65], v[64:65], v[188:189]
	v_pk_add_f32 v[66:67], v[66:67], v[190:191]
	global_load_dwordx4 v[4:7], v236, s[38:39]
	global_load_dwordx4 v[8:11], v236, s[38:39] offset:64
	global_load_dwordx4 v[12:15], v236, s[38:39] offset:256
	global_load_dwordx4 v[16:19], v236, s[38:39] offset:320
	v_add_u32_e32 v236, 0x10000, v236
	global_load_dwordx4 v[232:235], v236, s[38:39]
	global_load_dwordx4 v[176:179], v236, s[38:39] offset:64
	global_load_dwordx4 v[184:187], v236, s[38:39] offset:256
	global_load_dwordx4 v[188:191], v236, s[38:39] offset:320
	v_add_u32_e32 v236, 0x10000, v236
	s_branch .Lcch819_ret
